# P6 state scan: 4-chunk operand prefetch kept in flight across the back-edge - Q pairs of steps B/C in their own registers and unpacked in their step, counted vmcnt (18 / 26 / 26) instead of the loop-t
# baseline (speedup 1.0000x reference)
; #define GAS __attribute__((address_space(1)))
; #define LAS __attribute__((address_space(3)))
; __device__ __forceinline__ void scan_load(const bf16* PT, const bf16* QC, int c, ScanOps& o, int w, int fr, int fq) {
; #pragma unroll
;     for (int q = 0; q < 2; ++q) { const int tw = 2 * w + q, p0 = 16 * (tw >> 2), q0 = 16 * (tw & 3);
;         o.pf[q][0] = *(const GAS bf16x8*)(PT + (size_t)c * 4096 + ((q0 >> 4) * 2) * 512 + fr * 32 + fq * 8); o.pf[q][1] = *(const GAS bf16x8*)(PT + (size_t)c * 4096 + ((q0 >> 4) * 2 + 1) * 512 + fr * 32 + fq * 8);
;         o.qi[q] = *(const GAS v2u*)(QC + (size_t)c * 4096 + (p0 + fr) * 64 + q0 + 4 * fq); }
; __device__ __forceinline__ void rwkv_state_scan(Frame& F, int bh) {
;     LAS unsigned char* L = F.lds;
;     const int lane = F.lane, w = F.wave, fr = lane & 15, fq = lane >> 4;
;     const bf16* PT = (const bf16*)(F.ws + WS_PT) + (size_t)bh * NCH * 4096; const bf16* QC = (const bf16*)(F.ws + WS_QC) + (size_t)bh * NCH * 4096;
;     bf16* S = (bf16*)(F.ws + WS_S) + (size_t)bh * NCH * 4096;
;     f32x4 acc[2]; acc[0] = (f32x4){0.f, 0.f, 0.f, 0.f}; acc[1] = acc[0];
;     ScanOps o0, o1, o2, o3;
;     scan_load(PT, QC, 0, o0, w, fr, fq); scan_load(PT, QC, 1, o1, w, fr, fq); scan_load(PT, QC, 2, o2, w, fr, fq); scan_load(PT, QC, 3, o3, w, fr, fq);
; #pragma unroll 1
;     for (int c = 0; c < NCH; c += 4) {
;         const int n0 = (c + 4 < NCH) ? c + 4 : c, n1 = (c + 5 < NCH) ? c + 5 : c, n2 = (c + 6 < NCH) ? c + 6 : c, n3 = (c + 7 < NCH) ? c + 7 : c;
;         scan_step(L, S, c, o0, acc, w, fr, fq);     scan_load(PT, QC, n0, o0, w, fr, fq);
.LBB0_1528:
	s_load_dwordx2 s[2:3], s[72:73], 0x108
	s_waitcnt lgkmcnt(0)
	s_cmp_lt_i32 s2, 7
	s_cselect_b64 s[0:1], -1, 0
	s_cmp_gt_i32 s3, 6
	s_cselect_b64 s[2:3], -1, 0
	s_and_b64 s[0:1], s[0:1], s[2:3]
	s_andn2_b64 vcc, exec, s[0:1]
	s_cbranch_vccnz .LBB0_1621
	v_readlane_b32 s0, v254, 2
	v_readlane_b32 s1, v254, 3
	s_and_b32 s0, s0, 7
	s_lshl_b32 s16, s93, 3
	s_cmp_lg_u32 s0, 0
	s_mov_b32 s1, 0
	s_cbranch_scc1 .LBB0_1533
	v_readlane_b32 s2, v254, 2
	v_readlane_b32 s3, v254, 3
	s_ashr_i32 s2, s2, 3
	s_ashr_i32 s3, s2, 31
	s_lshl_b64 s[6:7], s[2:3], 19
	s_add_u32 s17, s80, s6
	s_addc_u32 s18, s81, s7
	s_add_u32 s0, s86, s6
	s_addc_u32 s5, s87, s7
	s_add_u32 s2, s0, 0x4000000
	s_addc_u32 s3, s5, 0
	s_lshl_b32 s4, s93, 1
	s_and_b32 s10, s4, 2
	s_or_b32 s11, s10, 1
	s_and_b32 s8, s16, 0x1ffffff0
	s_lshl_b32 s13, s10, 4
	s_lshl_b32 s15, s10, 10
	s_lshl_b32 s21, s11, 4
	s_lshl_b32 s20, s11, 10
	s_add_u32 s4, s0, 0x4006000
	v_and_b32_e32 v84, 15, v208
	v_ashrrev_i32_e32 v4, 4, v208
	s_addc_u32 s5, s5, 0
	v_or_b32_e32 v85, s8, v84
	v_lshlrev_b32_e32 v58, 2, v4
	s_add_u32 s14, s17, 0x6000
	v_mov_b32_e32 v57, 0
	v_lshlrev_b32_e32 v56, 7, v85
	v_ashrrev_i32_e32 v59, 31, v58
	s_addc_u32 s12, s18, 0
	s_lshl_b32 s0, s11, 5
	v_lshl_add_u64 v[2:3], s[2:3], 0, v[56:57]
	v_lshlrev_b64 v[48:49], 1, v[58:59]
	s_add_u32 s19, s17, 0x4000
	v_lshl_add_u64 v[60:61], v[2:3], 0, v[48:49]
	s_mov_b64 s[8:9], 0x4000
	s_addc_u32 s22, s18, 0
	s_lshl_b32 s23, s11, 11
	v_lshl_add_u64 v[2:3], v[60:61], 0, s[8:9]
	s_add_u32 s8, s19, s23
	s_addc_u32 s9, s22, 0
	v_lshlrev_b32_e32 v56, 6, v84
	v_lshlrev_b32_e32 v0, 3, v4
	v_lshl_add_u64 v[4:5], s[8:9], 0, v[56:57]
	s_lshl_b32 s8, s10, 5
	s_lshl_b32 s24, s10, 11
	s_add_u32 s10, s19, s24
	s_addc_u32 s11, s22, 0
	v_ashrrev_i32_e32 v1, 31, v0
	s_add_u32 s19, s17, 0x2000
	v_lshlrev_b64 v[62:63], 1, v[0:1]
	v_lshl_add_u64 v[0:1], s[10:11], 0, v[56:57]
	s_mov_b64 s[10:11], 0x2000
	s_addc_u32 s22, s18, 0
	v_lshl_add_u64 v[38:39], v[0:1], 0, v[62:63]
	v_lshl_add_u64 v[0:1], v[60:61], 0, s[10:11]
	s_add_u32 s10, s19, s23
	s_mov_b32 s9, s1
	s_addc_u32 s11, s22, 0
	v_lshl_add_u64 v[50:51], v[2:3], 0, s[0:1]
	v_lshl_add_u64 v[36:37], v[2:3], 0, s[8:9]
	v_lshl_add_u64 v[2:3], s[10:11], 0, v[56:57]
	s_add_u32 s10, s19, s24
	s_addc_u32 s11, s22, 0
	v_lshl_add_u64 v[44:45], v[0:1], 0, s[0:1]
	v_lshl_add_u64 v[54:55], v[0:1], 0, s[8:9]
	v_lshl_add_u64 v[0:1], s[10:11], 0, v[56:57]
	s_add_u32 s10, s17, s23
	s_addc_u32 s11, s18, 0
	v_lshl_add_u64 v[80:81], v[60:61], 0, s[8:9]
	s_add_u32 s8, s17, s24
	v_lshl_add_u64 v[64:65], v[0:1], 0, v[62:63]
	v_lshl_add_u64 v[0:1], s[10:11], 0, v[56:57]
	s_addc_u32 s9, s18, 0
	v_lshl_add_u64 v[76:77], v[0:1], 0, v[62:63]
	v_lshl_add_u64 v[0:1], s[8:9], 0, v[56:57]
	v_lshl_add_u64 v[46:47], v[2:3], 0, v[62:63]
	v_lshl_add_u64 v[82:83], v[0:1], 0, v[62:63]
	v_lshl_add_u64 v[52:53], v[4:5], 0, v[62:63]
	v_lshl_add_u64 v[66:67], v[60:61], 0, s[0:1]
	global_load_dwordx4 v[8:11], v[82:83], off
	global_load_dwordx4 v[0:3], v[82:83], off offset:1024
	global_load_dwordx2 v[68:69], v[80:81], off
	global_load_dwordx4 v[4:7], v[76:77], off offset:1024
	global_load_dwordx4 v[20:23], v[76:77], off
	global_load_dwordx2 v[74:75], v[66:67], off
	global_load_dwordx4 v[40:43], v[64:65], off
	global_load_dwordx4 v[12:15], v[64:65], off offset:1024
	global_load_dwordx2 v[140:141], v[54:55], off
	global_load_dwordx4 v[16:19], v[46:47], off offset:1024
	global_load_dwordx4 v[32:35], v[46:47], off
	global_load_dwordx2 v[146:147], v[44:45], off
	global_load_dwordx4 v[28:31], v[38:39], off
	global_load_dwordx4 v[24:27], v[38:39], off offset:1024
	global_load_dwordx2 v[142:143], v[36:37], off
	s_nop 0
	global_load_dwordx4 v[36:39], v[52:53], off offset:1024
	global_load_dwordx4 v[44:47], v[52:53], off
	global_load_dwordx2 v[144:145], v[50:51], off
	s_movk_i32 s0, 0x90
	v_mul_lo_u32 v51, v85, s0
	s_and_b32 s0, s79, 64
	s_or_b32 s6, s6, s0
	s_lshl_b32 s0, s79, 3
	s_and_b32 s0, s0, 0xfffffc00
	v_lshl_add_u64 v[48:49], s[6:7], 0, v[48:49]
	v_or_b32_e32 v56, s0, v56
	v_add_lshl_u32 v81, v58, s13, 1
	v_lshl_add_u64 v[48:49], v[56:57], 1, v[48:49]
	v_lshlrev_b32_e32 v50, 5, v84
	v_lshlrev_b32_e32 v52, 6, v85
	v_add_u32_e32 v80, 0, v51
	v_add_u32_e32 v51, 32, v81
	v_and_b32_e32 v53, -16, v208
	v_lshl_add_u64 v[48:49], s[86:87], 0, v[48:49]
	s_mov_b64 s[6:7], 0x200000
	v_lshl_add_u64 v[64:65], v[48:49], 0, s[6:7]
	s_mov_b32 s26, -4
	s_lshl_b32 s19, s15, 1
	v_lshlrev_b32_e32 v56, 1, v50
	s_lshl_b32 s20, s20, 1
	v_lshlrev_b32_e32 v66, 1, v52
	s_lshl_b32 s6, s13, 1
	s_lshl_b32 s8, s21, 1
	s_movk_i32 s21, 0x6000
	v_add_u32_e32 v82, v80, v51
	v_add_u32_e32 v83, v80, v53
	s_movk_i32 s22, 0x2000
	s_movk_i32 s23, 0x4000
	s_mov_b64 s[10:11], 0x8000
	s_mov_b32 s7, s1
	s_mov_b32 s9, s1
	s_mov_b32 s24, 0
	v_mov_b32_e32 v48, v57
	v_mov_b32_e32 v49, v57
	v_mov_b32_e32 v50, v57
	v_mov_b32_e32 v51, v57
	v_mov_b32_e32 v52, v57
	v_mov_b32_e32 v53, v57
	v_mov_b32_e32 v54, v57
	v_mov_b32_e32 v55, v57
	s_waitcnt vmcnt(0)
.LBB0_1531:
	s_add_i32 s25, s26, 4
	v_mov_b32_e32 v67, v57
	s_add_u32 s28, s14, s19
	s_nop 2
	v_cvt_pk_bf16_f32 v118, v48, v49
	v_cvt_pk_bf16_f32 v119, v50, v51
	s_waitcnt vmcnt(18)
	v_lshlrev_b32_e32 v48, 16, v68
	v_and_b32_e32 v49, 0xffff0000, v68
	v_lshlrev_b32_e32 v50, 16, v69
	v_and_b32_e32 v51, 0xffff0000, v69
	v_lshl_add_u64 v[68:69], s[4:5], 0, v[66:67]
	s_addc_u32 s29, s12, 0
	v_cvt_pk_bf16_f32 v116, v52, v53
	v_cvt_pk_bf16_f32 v117, v54, v55
	v_add_u32_e32 v128, v80, v81
	v_add_co_u32_e32 v120, vcc, s22, v64
	v_lshl_add_u64 v[68:69], v[58:59], 1, v[68:69]
	s_add_u32 s4, s14, s20
	v_addc_co_u32_e32 v121, vcc, 0, v65, vcc


; #define LAS __attribute__((address_space(3)))
; __device__ __forceinline__ void st4_lds(LAS unsigned char* p, f32x4 v) { v2u w; w.x = pk2(v[0], v[1]); w.y = pk2(v[2], v[3]); *(LAS v2u*)p = w; }
; __device__ __forceinline__ void st4_g(bf16* p, f32x4 v) { v2u w; w.x = pk2(v[0], v[1]); w.y = pk2(v[2], v[3]); *(GAS v2u*)p = w; }
; __device__ __forceinline__ void scan_step(LAS unsigned char* L, bf16* S, int c, const ScanOps& o, f32x4 (&acc)[2], int w, int fr, int fq) {
; #pragma unroll
;     for (int q = 0; q < 2; ++q) { const int tw = 2 * w + q, p0 = 16 * (tw >> 2), q0 = 16 * (tw & 3);
;         st4_g(S + (size_t)c * 4096 + (p0 + fr) * 64 + q0 + 4 * fq, acc[q]);
;         st4_lds(L + (c & 1) * ARR + (p0 + fr) * LD + (q0 + 4 * fq) * 2, acc[q]); }
	ds_write_b64 v128, v[116:117]
	ds_write_b64 v82, v[118:119]
	v_lshl_add_u64 v[72:73], v[68:69], 0, s[6:7]
	v_lshl_add_u64 v[68:69], v[68:69], 0, s[8:9]
	s_addc_u32 s5, s12, 0
	s_add_i32 s0, s26, 8


; #define GAS __attribute__((address_space(1)))
; #define LAS __attribute__((address_space(3)))
; __device__ __forceinline__ void st4_lds(LAS unsigned char* p, f32x4 v) { v2u w; w.x = pk2(v[0], v[1]); w.y = pk2(v[2], v[3]); *(LAS v2u*)p = w; }
; __device__ __forceinline__ void st4_g(bf16* p, f32x4 v) { v2u w; w.x = pk2(v[0], v[1]); w.y = pk2(v[2], v[3]); *(GAS v2u*)p = w; }
; #define LBAR() asm volatile("s_waitcnt lgkmcnt(0)\n\ts_barrier" ::: "memory")
; __device__ __forceinline__ void scan_load(const bf16* PT, const bf16* QC, int c, ScanOps& o, int w, int fr, int fq) {
; #pragma unroll
;     for (int q = 0; q < 2; ++q) { const int tw = 2 * w + q, p0 = 16 * (tw >> 2), q0 = 16 * (tw & 3);
;         o.pf[q][0] = *(const GAS bf16x8*)(PT + (size_t)c * 4096 + ((q0 >> 4) * 2) * 512 + fr * 32 + fq * 8); o.pf[q][1] = *(const GAS bf16x8*)(PT + (size_t)c * 4096 + ((q0 >> 4) * 2 + 1) * 512 + fr * 32 + fq * 8);
;         o.qi[q] = *(const GAS v2u*)(QC + (size_t)c * 4096 + (p0 + fr) * 64 + q0 + 4 * fq); }
; }
; __device__ __forceinline__ void scan_step(LAS unsigned char* L, bf16* S, int c, const ScanOps& o, f32x4 (&acc)[2], int w, int fr, int fq) {
; #pragma unroll
;     for (int q = 0; q < 2; ++q) { const int tw = 2 * w + q, p0 = 16 * (tw >> 2), q0 = 16 * (tw & 3);
;         st4_g(S + (size_t)c * 4096 + (p0 + fr) * 64 + q0 + 4 * fq, acc[q]);
;         st4_lds(L + (c & 1) * ARR + (p0 + fr) * LD + (q0 + 4 * fq) * 2, acc[q]); }
;     LBAR();
	v_add_co_u32_e32 v122, vcc, s23, v64
	v_lshl_add_u64 v[70:71], s[28:29], 0, v[56:57]
	global_load_dwordx2 v[124:125], v[72:73], off
	global_load_dwordx2 v[126:127], v[68:69], off
	v_lshl_add_u64 v[68:69], s[4:5], 0, v[56:57]
	s_cmp_lt_u32 s25, 60
	v_addc_co_u32_e32 v123, vcc, 0, v65, vcc
	v_lshl_add_u64 v[70:71], v[70:71], 0, v[62:63]
	v_lshl_add_u64 v[68:69], v[68:69], 0, v[62:63]
	s_cselect_b64 s[4:5], -1, 0
	global_load_dwordx4 v[100:103], v[70:71], off
	global_load_dwordx4 v[104:107], v[70:71], off offset:1024
	global_load_dwordx4 v[108:111], v[68:69], off
	global_load_dwordx4 v[112:115], v[68:69], off offset:1024
	s_and_b64 vcc, s[4:5], exec
	global_store_dwordx2 v[64:65], v[116:117], off
	global_store_dwordx2 v[64:65], v[118:119], off offset:32
	s_cselect_b32 s0, s0, s25
	s_waitcnt lgkmcnt(0)
	s_barrier
	v_lshlrev_b32_e32 v52, 16, v74
	v_and_b32_e32 v53, 0xffff0000, v74
	v_lshlrev_b32_e32 v54, 16, v75
	v_and_b32_e32 v55, 0xffff0000, v75


; #define LAS __attribute__((address_space(3)))
; __device__ __forceinline__ void scan_step(LAS unsigned char* L, bf16* S, int c, const ScanOps& o, f32x4 (&acc)[2], int w, int fr, int fq) {
;     ...
; #pragma unroll
;     for (int q = 0; q < 2; ++q) { const int tw = 2 * w + q, p0 = 16 * (tw >> 2);
;         const LAS unsigned char* sp = L + (c & 1) * ARR + (p0 + fr) * LD + fq * 16;
;         const bf16x8 s0 = *(const LAS bf16x8*)sp, s1 = *(const LAS bf16x8*)(sp + 64);
;         f32x4 a = (f32x4){bflo(o.qi[q].x), bfhi(o.qi[q].x), bflo(o.qi[q].y), bfhi(o.qi[q].y)};
;         a = __builtin_amdgcn_mfma_f32_16x16x32_bf16(o.pf[q][0], s0, a, 0, 0, 0);
;         a = __builtin_amdgcn_mfma_f32_16x16x32_bf16(o.pf[q][1], s1, a, 0, 0, 0);
;         acc[q] = a; }
	s_lshl_b32 s0, s0, 13
	ds_read_b128 v[70:73], v83
	ds_read_b128 v[74:77], v83 offset:64
	s_add_u32 s12, s17, s0
	v_lshl_add_u64 v[68:69], v[60:61], 0, s[0:1]
	s_addc_u32 s0, s18, 0
	s_add_u32 s4, s12, s19
	s_waitcnt lgkmcnt(1)
	v_mfma_f32_16x16x32_bf16 v[48:51], v[8:11], v[70:73], v[48:51]
	s_addc_u32 s5, s0, 0
	s_add_u32 s26, s12, s20
	s_addc_u32 s27, s0, 0
	v_mfma_f32_16x16x32_bf16 v[20:23], v[20:23], v[70:73], v[52:55]
	s_add_i32 s0, s24, 0x5000
	s_cmp_lt_u32 s25, 59
	s_mov_b32 s15, s1
	v_lshl_add_u64 v[52:53], s[26:27], 0, v[56:57]
	s_waitcnt lgkmcnt(0)
	v_mfma_f32_16x16x32_bf16 v[48:51], v[0:3], v[74:77], v[48:51]
	s_cselect_b32 s14, s0, s24
	v_lshl_add_u64 v[72:73], v[52:53], 0, v[62:63]
	v_lshl_add_u64 v[8:9], s[4:5], 0, v[56:57]
	v_mfma_f32_16x16x32_bf16 v[52:55], v[4:7], v[74:77], v[20:23]
	s_lshl_b64 s[4:5], s[14:15], 1
	s_add_u32 s0, s17, s4


; #define GAS __attribute__((address_space(1)))
; #define LAS __attribute__((address_space(3)))
; #define LBAR() asm volatile("s_waitcnt lgkmcnt(0)\n\ts_barrier" ::: "memory")
; __device__ __forceinline__ void scan_load(const bf16* PT, const bf16* QC, int c, ScanOps& o, int w, int fr, int fq) {
; #pragma unroll
;     for (int q = 0; q < 2; ++q) { const int tw = 2 * w + q, p0 = 16 * (tw >> 2), q0 = 16 * (tw & 3);
;         o.pf[q][0] = *(const GAS bf16x8*)(PT + (size_t)c * 4096 + ((q0 >> 4) * 2) * 512 + fr * 32 + fq * 8); o.pf[q][1] = *(const GAS bf16x8*)(PT + (size_t)c * 4096 + ((q0 >> 4) * 2 + 1) * 512 + fr * 32 + fq * 8);
;         o.qi[q] = *(const GAS v2u*)(QC + (size_t)c * 4096 + (p0 + fr) * 64 + q0 + 4 * fq); }
; }
; __device__ __forceinline__ void scan_step(LAS unsigned char* L, bf16* S, int c, const ScanOps& o, f32x4 (&acc)[2], int w, int fr, int fq) {
; #pragma unroll
;     for (int q = 0; q < 2; ++q) { const int tw = 2 * w + q, p0 = 16 * (tw >> 2), q0 = 16 * (tw & 3);
;         st4_g(S + (size_t)c * 4096 + (p0 + fr) * 64 + q0 + 4 * fq, acc[q]);
;         st4_lds(L + (c & 1) * ARR + (p0 + fr) * LD + (q0 + 4 * fq) * 2, acc[q]); }
;     LBAR();
; #pragma unroll
;     for (int q = 0; q < 2; ++q) { const int tw = 2 * w + q, p0 = 16 * (tw >> 2);
;         const LAS unsigned char* sp = L + (c & 1) * ARR + (p0 + fr) * LD + fq * 16;
;         const bf16x8 s0 = *(const LAS bf16x8*)sp, s1 = *(const LAS bf16x8*)(sp + 64);
;         f32x4 a = (f32x4){bflo(o.qi[q].x), bfhi(o.qi[q].x), bflo(o.qi[q].y), bfhi(o.qi[q].y)};
;         a = __builtin_amdgcn_mfma_f32_16x16x32_bf16(o.pf[q][0], s0, a, 0, 0, 0);
;         a = __builtin_amdgcn_mfma_f32_16x16x32_bf16(o.pf[q][1], s1, a, 0, 0, 0);
;         acc[q] = a; }
; __device__ __forceinline__ void rwkv_state_scan(Frame& F, int bh) {
;     ...
;     for (int c = 0; c < NCH; c += 4) {
;         const int n0 = (c + 4 < NCH) ? c + 4 : c, n1 = (c + 5 < NCH) ? c + 5 : c, n2 = (c + 6 < NCH) ? c + 6 : c, n3 = (c + 7 < NCH) ? c + 7 : c;
;         scan_step(L, S, c, o0, acc, w, fr, fq);     scan_load(PT, QC, n0, o0, w, fr, fq);
;         scan_step(L, S, c + 1, o1, acc, w, fr, fq); scan_load(PT, QC, n1, o1, w, fr, fq);
;         scan_step(L, S, c + 2, o2, acc, w, fr, fq); scan_load(PT, QC, n2, o2, w, fr, fq);
;         scan_step(L, S, c + 3, o3, acc, w, fr, fq); scan_load(PT, QC, n3, o3, w, fr, fq);
;     }
;     LBAR();
	v_lshl_add_u64 v[78:79], v[68:69], 0, s[6:7]
	v_lshl_add_u64 v[70:71], v[8:9], 0, v[62:63]
	s_addc_u32 s12, s18, s5
	v_lshl_add_u64 v[116:117], v[68:69], 0, s[8:9]
	global_load_dwordx2 v[68:69], v[78:79], off
	global_load_dwordx4 v[8:11], v[70:71], off
	global_load_dwordx4 v[0:3], v[70:71], off offset:1024
	global_load_dwordx4 v[20:23], v[72:73], off
	global_load_dwordx4 v[4:7], v[72:73], off offset:1024
	global_load_dwordx2 v[74:75], v[116:117], off
	v_lshl_add_u64 v[70:71], v[60:61], 0, s[4:5]
	s_add_u32 s4, s0, s19
	v_cvt_pk_bf16_f32 v48, v48, v49
	v_cvt_pk_bf16_f32 v49, v50, v51
	v_cvt_pk_bf16_f32 v50, v52, v53
	v_cvt_pk_bf16_f32 v51, v54, v55
	s_addc_u32 s5, s12, 0
	global_store_dwordx2 v[120:121], v[48:49], off
	ds_write_b64 v128, v[48:49] offset:9216
	global_store_dwordx2 v[120:121], v[50:51], off offset:32
	ds_write_b64 v82, v[50:51] offset:9216
	v_lshl_add_u64 v[48:49], s[4:5], 0, v[56:57]
	s_waitcnt lgkmcnt(0)
	s_barrier
	v_lshl_add_u64 v[78:79], v[48:49], 0, v[62:63]
	ds_read_b128 v[48:51], v83 offset:9216
	ds_read_b128 v[52:55], v83 offset:9280
	s_add_u32 s14, s0, s20
	s_addc_u32 s15, s12, 0
	s_add_i32 s0, s24, 0x6000
	s_cmp_lt_u32 s25, 58
	s_waitcnt vmcnt(26)
	v_lshlrev_b32_e32 v84, 16, v140
	v_and_b32_e32 v85, 0xffff0000, v140
	v_lshlrev_b32_e32 v86, 16, v141
	v_and_b32_e32 v87, 0xffff0000, v141
	v_lshlrev_b32_e32 v88, 16, v146
	v_and_b32_e32 v89, 0xffff0000, v146
	v_lshlrev_b32_e32 v90, 16, v147
	v_and_b32_e32 v91, 0xffff0000, v147
	s_waitcnt lgkmcnt(1)
	v_mfma_f32_16x16x32_bf16 v[40:43], v[40:43], v[48:51], v[84:87]
	s_mov_b32 s13, s1
	s_cselect_b32 s12, s0, s24
	s_lshl_b64 s[4:5], s[12:13], 1
	v_mfma_f32_16x16x32_bf16 v[48:51], v[32:35], v[48:51], v[88:91]
	v_lshl_add_u64 v[84:85], v[60:61], 0, s[4:5]
	v_lshl_add_u64 v[72:73], v[70:71], 0, s[6:7]
	v_lshl_add_u64 v[76:77], v[70:71], 0, s[8:9]
	v_lshl_add_u64 v[88:89], v[84:85], 0, s[6:7]
	v_lshl_add_u64 v[90:91], v[84:85], 0, s[8:9]
	s_waitcnt lgkmcnt(0)
	v_mfma_f32_16x16x32_bf16 v[84:87], v[12:15], v[52:55], v[40:43]
	global_load_dwordx2 v[140:141], v[72:73], off
	v_lshl_add_u64 v[72:73], s[14:15], 0, v[56:57]
	v_lshl_add_u64 v[72:73], v[72:73], 0, v[62:63]
	v_mfma_f32_16x16x32_bf16 v[48:51], v[16:19], v[52:55], v[48:51]
	global_load_dwordx4 v[40:43], v[78:79], off
	global_load_dwordx4 v[32:35], v[72:73], off
	s_nop 1
	v_cvt_pk_bf16_f32 v52, v84, v85
	v_cvt_pk_bf16_f32 v53, v86, v87
	global_load_dwordx4 v[12:15], v[78:79], off offset:1024
	global_load_dwordx4 v[16:19], v[72:73], off offset:1024
	s_nop 0
	global_load_dwordx2 v[146:147], v[76:77], off
	v_cvt_pk_bf16_f32 v48, v48, v49
	v_cvt_pk_bf16_f32 v49, v50, v51
	global_store_dwordx2 v[122:123], v[52:53], off
	ds_write_b64 v128, v[52:53]
	global_store_dwordx2 v[122:123], v[48:49], off offset:32
	ds_write_b64 v82, v[48:49]
	s_waitcnt lgkmcnt(0)
	s_barrier
	ds_read_b128 v[48:51], v83
	ds_read_b128 v[52:55], v83 offset:64
	s_add_u32 s0, s17, s4
	s_addc_u32 s13, s18, s5
	s_add_u32 s4, s0, s19
	s_addc_u32 s5, s13, 0
	s_waitcnt vmcnt(26)
	v_lshlrev_b32_e32 v92, 16, v142
	v_and_b32_e32 v93, 0xffff0000, v142
	v_lshlrev_b32_e32 v94, 16, v143
	v_and_b32_e32 v95, 0xffff0000, v143
	v_lshlrev_b32_e32 v96, 16, v144
	v_and_b32_e32 v97, 0xffff0000, v144
	v_lshlrev_b32_e32 v98, 16, v145
	v_and_b32_e32 v99, 0xffff0000, v145
	s_waitcnt lgkmcnt(1)
	v_mfma_f32_16x16x32_bf16 v[28:31], v[28:31], v[48:51], v[92:95]
	s_add_u32 s12, s0, s20
	v_lshl_add_u64 v[72:73], s[4:5], 0, v[56:57]
	s_addc_u32 s13, s13, 0
	v_mfma_f32_16x16x32_bf16 v[48:51], v[44:47], v[48:51], v[96:99]
	v_lshl_add_u64 v[92:93], v[72:73], 0, v[62:63]
	v_lshl_add_u64 v[44:45], s[12:13], 0, v[56:57]
	v_lshl_add_u64 v[94:95], v[44:45], 0, v[62:63]
	s_waitcnt lgkmcnt(0)
	v_mfma_f32_16x16x32_bf16 v[84:87], v[24:27], v[52:55], v[28:31]
	global_load_dwordx2 v[142:143], v[88:89], off
	s_nop 1
	global_load_dwordx4 v[28:31], v[92:93], off
	global_load_dwordx4 v[44:47], v[94:95], off
	s_waitcnt vmcnt(25)
	v_lshlrev_b32_e32 v88, 16, v126
	v_and_b32_e32 v89, 0xffff0000, v126
	v_mfma_f32_16x16x32_bf16 v[48:51], v[36:39], v[52:55], v[48:51]
	global_load_dwordx4 v[24:27], v[92:93], off offset:1024
	global_load_dwordx4 v[36:39], v[94:95], off offset:1024
	global_load_dwordx2 v[144:145], v[90:91], off
	v_add_co_u32_e64 v52, s[4:5], s21, v64
	v_cvt_pk_bf16_f32 v54, v84, v85
	s_nop 0
	v_addc_co_u32_e64 v53, s[4:5], 0, v65, s[4:5]
	v_cvt_pk_bf16_f32 v55, v86, v87
	v_cvt_pk_bf16_f32 v48, v48, v49
	v_cvt_pk_bf16_f32 v49, v50, v51
	global_store_dwordx2 v[52:53], v[54:55], off
	ds_write_b64 v128, v[54:55] offset:9216
	global_store_dwordx2 v[52:53], v[48:49], off offset:32
	ds_write_b64 v82, v[48:49] offset:9216
	s_waitcnt lgkmcnt(0)
	s_barrier
	ds_read_b128 v[48:51], v83 offset:9216
	ds_read_b128 v[84:87], v83 offset:9280
	v_lshlrev_b32_e32 v52, 16, v124
	v_and_b32_e32 v53, 0xffff0000, v124
	v_lshlrev_b32_e32 v54, 16, v125
	v_and_b32_e32 v55, 0xffff0000, v125
	v_lshlrev_b32_e32 v90, 16, v127
	v_and_b32_e32 v91, 0xffff0000, v127
	s_add_i32 s0, s24, 0x7000
	s_waitcnt vmcnt(29) lgkmcnt(1)
	v_mfma_f32_16x16x32_bf16 v[52:55], v[100:103], v[48:51], v[52:55]
	s_cmp_lt_u32 s25, 57
	s_cselect_b32 s0, s0, s24
	s_lshl_b64 s[4:5], s[0:1], 1
	s_waitcnt vmcnt(27)
	v_mfma_f32_16x16x32_bf16 v[48:51], v[108:111], v[48:51], v[88:91]
	s_add_u32 s14, s17, s4
	s_addc_u32 s12, s18, s5
	s_add_u32 s4, s2, s4
	s_waitcnt lgkmcnt(0)
	v_mfma_f32_16x16x32_bf16 v[52:55], v[104:107], v[84:87], v[52:55]
	s_mov_b32 s26, s25
	v_lshl_add_u64 v[64:65], v[64:65], 0, s[10:11]
	s_addc_u32 s5, s3, s5
	s_waitcnt vmcnt(26)
	v_mfma_f32_16x16x32_bf16 v[48:51], v[112:115], v[84:87], v[48:51]
	s_addk_i32 s24, 0x4000
	s_cbranch_vccnz .LBB0_1531
	s_waitcnt vmcnt(0)
	s_waitcnt lgkmcnt(0)
	s_barrier
